# speedup vs baseline: 1.0056x; 1.0035x over previous
; __device__ __forceinline__ int ptid() { int t = __builtin_amdgcn_workitem_id_x(); asm volatile("" : "+v"(t)); return t; }
; __device__ __forceinline__ float bflo(unsigned u) { return __uint_as_float(u << 16); }
; __device__ __forceinline__ float bfhi(unsigned u) { return __uint_as_float(u & 0xffff0000u); }
; static __device__ __forceinline__ void attn_item(const Params& p, int head, int j, char* smraw) {
;     ...
;   const int tid = ptid(), lane = tid & 63, w = tid >> 6, l15 = lane & 15, quad = lane >> 4;
;   u16* sK[2]; u16* sV[2];
;   sK[0] = (u16*)smraw; sV[0] = sK[0] + 64 * 128; sK[1] = sV[0] + 64 * 64; sV[1] = sK[1] + 64 * 128;
;   const int qrow0 = tseq0 + qb * 128 + w * 32;
;   bf16x8 qf[2][3];
; #pragma unroll
;   for (int qt = 0; qt < 2; ++qt)
; #pragma unroll
;     for (int ks = 0; ks < 3; ++ks)
;     {
;       const u32x4 qraw = *(const u32x4*)(Qb + (size_t)(qrow0 + qt * 16 + l15) * 768 + head * 96 + ks * 32 + quad * 8);
;       constexpr float CQ = 0.10206207261596577f * 1.4426950408889634f;
;       u32x4 qs;
; #pragma unroll
;       for (int e = 0; e < 4; ++e) qs[e] = cvtpk(bflo(qraw[e]) * CQ, bfhi(qraw[e]) * CQ);
;       qf[qt][ks] = *(bf16x8*)&qs;
;     }
;     ...
;   float mrun[2] = {0.f, 0.f}, lrun[2] = {0.f, 0.f};
.LBB0_373:
	s_or_b64 exec, exec, s[0:1]
	s_waitcnt lgkmcnt(0)
	s_barrier
	ds_read_b32 v0, v176
	s_mov_b64 s[0:1], -1
	s_waitcnt lgkmcnt(0)
	s_barrier
	v_cmp_lt_i32_e32 vcc, s22, v0
	v_readfirstlane_b32 s3, v0
	s_cbranch_vccnz .LBB0_368
	s_lshl_b32 s0, s3, 7
	s_cmpk_lt_i32 s3, 0x200
	s_cselect_b32 s1, 63, 15
	s_cselect_b32 s12, s23, 0x7ffff800
	s_cselect_b32 s13, s24, 0xffff0000
	s_cselect_b32 s2, 0x80, 32
	s_and_b32 s1, s1, s3
	s_and_b32 s0, s12, s0
	s_add_i32 s0, s0, s13
	s_waitcnt vmcnt(24)
	v_mov_b32_e32 v70, v174
	s_lshl_b32 s1, s1, 7
	s_add_i32 s1, s0, s1
	s_waitcnt vmcnt(23)
	v_and_b32_e32 v71, 15, v70
	v_ashrrev_i32_e32 v0, 1, v70
	v_bfe_u32 v178, v70, 4, 2
	v_and_b32_e32 v0, 0xffffffe0, v0
	v_or_b32_e32 v1, s1, v71
	v_add_u32_e32 v130, v1, v0
	v_lshlrev_b32_e32 v128, 4, v178
	v_lshl_add_u64 v[12:13], s[46:47], 0, v[128:129]
	v_or_b32_e32 v132, 16, v130
	v_mad_i64_i32 v[8:9], s[12:13], v130, s25, v[12:13]
	v_mad_i64_i32 v[20:21], s[12:13], v132, s25, v[12:13]
	global_load_dwordx4 v[0:3], v[8:9], off
	global_load_dwordx4 v[4:7], v[8:9], off offset:64
	s_nop 0
	global_load_dwordx4 v[8:11], v[8:9], off offset:128
	s_nop 0
	global_load_dwordx4 v[12:15], v[20:21], off
	global_load_dwordx4 v[16:19], v[20:21], off offset:64
	s_ashr_i32 s1, s0, 31
	global_load_dwordx4 v[20:23], v[20:21], off offset:128
	s_mul_i32 s12, s0, 0x600
	s_mul_hi_i32 s3, s0, 0x600
	s_add_u32 s12, s64, s12
	s_addc_u32 s13, s65, s3
	s_lshl_b64 s[50:51], s[0:1], 1
	v_ashrrev_i32_e32 v77, 3, v70
	s_waitcnt vmcnt(28)
	v_lshrrev_b32_e32 v72, 4, v70
	v_ashrrev_i32_e32 v131, 31, v130
	v_ashrrev_i32_e32 v133, 31, v132
	s_mov_b32 s3, 3
	v_mov_b32_e32 v189, 0
	v_mov_b32_e32 v190, 0
	v_mov_b32_e32 v232, 0x80000000
	v_mov_b32_e32 v233, 0x80000000
	v_mov_b32_e32 v234, 0x80000000
	v_mov_b32_e32 v235, 0x80000000
	v_mov_b32_e32 v236, 0x80000000
	v_mov_b32_e32 v237, 0x80000000
	v_mov_b32_e32 v238, 0x80000000
	v_mov_b32_e32 v239, 0x80000000
	s_waitcnt vmcnt(5)
	v_lshlrev_b32_e32 v24, 16, v0
	v_and_b32_e32 v25, 0xffff0000, v0
	v_lshlrev_b32_e32 v0, 16, v1
	v_and_b32_e32 v1, 0xffff0000, v1
	v_lshlrev_b32_e32 v26, 16, v2
	v_and_b32_e32 v27, 0xffff0000, v2
	v_pk_mul_f32 v[24:25], v[24:25], s[6:7] op_sel_hi:[1,0]
	s_waitcnt vmcnt(2)
	v_lshlrev_b32_e32 v48, 16, v12
	v_and_b32_e32 v49, 0xffff0000, v12
	v_lshlrev_b32_e32 v2, 16, v3
	v_and_b32_e32 v3, 0xffff0000, v3
	v_pk_mul_f32 v[36:37], v[0:1], s[6:7] op_sel_hi:[1,0]
	v_pk_mul_f32 v[26:27], v[26:27], s[6:7] op_sel_hi:[1,0]
	v_lshlrev_b32_e32 v12, 16, v13
	v_and_b32_e32 v13, 0xffff0000, v13
	v_lshlrev_b32_e32 v50, 16, v14
	v_and_b32_e32 v51, 0xffff0000, v14
	v_cvt_pk_bf16_f32 v0, v24, v25
	v_pk_mul_f32 v[24:25], v[48:49], s[6:7] op_sel_hi:[1,0]
	v_pk_mul_f32 v[38:39], v[2:3], s[6:7] op_sel_hi:[1,0]
	v_cvt_pk_bf16_f32 v2, v26, v27
	v_pk_mul_f32 v[26:27], v[12:13], s[6:7] op_sel_hi:[1,0]
	v_cvt_pk_bf16_f32 v12, v24, v25
	v_pk_mul_f32 v[24:25], v[50:51], s[6:7] op_sel_hi:[1,0]
	v_lshlrev_b32_e32 v28, 16, v4
	v_cvt_pk_bf16_f32 v14, v24, v25
	v_lshlrev_b32_e32 v24, 16, v15
	v_and_b32_e32 v25, 0xffff0000, v15
	v_pk_mul_f32 v[24:25], v[24:25], s[6:7] op_sel_hi:[1,0]
	v_and_b32_e32 v29, 0xffff0000, v4
	v_cvt_pk_bf16_f32 v15, v24, v25
	s_waitcnt vmcnt(1)
	v_lshlrev_b32_e32 v24, 16, v16
	v_and_b32_e32 v25, 0xffff0000, v16
	v_pk_mul_f32 v[24:25], v[24:25], s[6:7] op_sel_hi:[1,0]
	v_lshlrev_b32_e32 v4, 16, v5
	v_cvt_pk_bf16_f32 v16, v24, v25
	v_lshlrev_b32_e32 v24, 16, v17
	v_and_b32_e32 v25, 0xffff0000, v17
	v_pk_mul_f32 v[24:25], v[24:25], s[6:7] op_sel_hi:[1,0]
	v_and_b32_e32 v5, 0xffff0000, v5
	v_cvt_pk_bf16_f32 v17, v24, v25
	v_lshlrev_b32_e32 v24, 16, v18
	v_and_b32_e32 v25, 0xffff0000, v18
	v_pk_mul_f32 v[24:25], v[24:25], s[6:7] op_sel_hi:[1,0]
	v_pk_mul_f32 v[40:41], v[4:5], s[6:7] op_sel_hi:[1,0]
	v_cvt_pk_bf16_f32 v18, v24, v25
	v_lshlrev_b32_e32 v24, 16, v19
	v_and_b32_e32 v25, 0xffff0000, v19
	v_pk_mul_f32 v[24:25], v[24:25], s[6:7] op_sel_hi:[1,0]
	v_cvt_pk_bf16_f32 v5, v40, v41
	v_cvt_pk_bf16_f32 v19, v24, v25
	s_waitcnt vmcnt(0)
	v_lshlrev_b32_e32 v24, 16, v20
	v_and_b32_e32 v25, 0xffff0000, v20
	v_pk_mul_f32 v[24:25], v[24:25], s[6:7] op_sel_hi:[1,0]
	v_lshlrev_b32_e32 v40, 16, v21
	v_and_b32_e32 v41, 0xffff0000, v21
	v_mul_hi_i32 v21, v70, s26
	v_cvt_pk_bf16_f32 v20, v24, v25
	v_lshrrev_b32_e32 v24, 31, v21
	v_ashrrev_i32_e32 v21, 1, v21
	v_lshlrev_b32_e32 v34, 16, v10
	v_and_b32_e32 v35, 0xffff0000, v10
	v_lshlrev_b32_e32 v10, 16, v11
	v_and_b32_e32 v11, 0xffff0000, v11
	v_add_u32_e32 v74, v21, v24
	v_pk_mul_f32 v[46:47], v[10:11], s[6:7] op_sel_hi:[1,0]
	v_mul_lo_u32 v21, v74, 12
	v_cvt_pk_bf16_f32 v11, v46, v47
	v_sub_u32_e32 v46, v70, v21
	v_add_u32_e32 v21, 0x100, v70
	v_mul_hi_i32 v25, v21, s26
	v_lshlrev_b32_e32 v32, 16, v8
	v_and_b32_e32 v33, 0xffff0000, v8
	v_lshlrev_b32_e32 v8, 16, v9
	v_and_b32_e32 v9, 0xffff0000, v9
	v_cvt_pk_bf16_f32 v13, v26, v27
	v_lshrrev_b32_e32 v26, 31, v25
	v_ashrrev_i32_e32 v25, 1, v25
	v_pk_mul_f32 v[44:45], v[8:9], s[6:7] op_sel_hi:[1,0]
	v_add_u32_e32 v75, v25, v26
	v_cvt_pk_bf16_f32 v9, v44, v45
	v_mul_lo_u32 v25, v75, 12
	v_pk_mul_f32 v[44:45], v[40:41], s[6:7] op_sel_hi:[1,0]
	v_sub_u32_e32 v47, v21, v25
	v_ashrrev_i32_e32 v78, 3, v21
	v_cvt_pk_bf16_f32 v21, v44, v45
	v_lshlrev_b32_e32 v44, 16, v22
	v_and_b32_e32 v45, 0xffff0000, v22
	v_pk_mul_f32 v[44:45], v[44:45], s[6:7] op_sel_hi:[1,0]
	v_add_u32_e32 v25, 0x200, v70
	v_cvt_pk_bf16_f32 v22, v44, v45
	v_lshlrev_b32_e32 v44, 16, v23
	v_and_b32_e32 v45, 0xffff0000, v23
	v_pk_mul_f32 v[44:45], v[44:45], s[6:7] op_sel_hi:[1,0]
	v_pk_mul_f32 v[28:29], v[28:29], s[6:7] op_sel_hi:[1,0]
	v_cvt_pk_bf16_f32 v23, v44, v45
	v_lshlrev_b32_e32 v44, 2, v74
; static __device__ __forceinline__ void attn_item(const Params& p, int head, int j, char* smraw) {
;     ...
;   int krow[3], kcol[3], klds[3];
; #pragma unroll
;   for (int i = 0; i < 3; ++i) {
;     const int c = tid + 256 * i, kv = c / 12, kc = c % 12;
;     const int rho = (kv & 32) | (((kv >> 2) & 1) << 4) | (((kv >> 3) & 3) << 2) | (kv & 3);
;     krow[i] = kv; kcol[i] = kc * 8; klds[i] = rho * 128 + ((kc ^ (rho & 15)) << 3);
;   }
;   const u16* Kg = Kb + (size_t)tseq0 * 768 + head * 96;
;   const u16* Vg = Vt + (size_t)(head * 64) * T + tseq0;
;   u32x4 rkA[3], rvA[2], rkB[3], rvB[2];
;     ...
;   f32x4 oacc[4][2];
; #pragma unroll
;   for (int a = 0; a < 4; ++a)
; #pragma unroll
;     for (int b = 0; b < 2; ++b) oacc[a][b] = f32x4{0.f, 0.f, 0.f, 0.f};
;     ...
;   ATT_LOAD(rkA, rvA, 0); ATT_LOAD(rkB, rvB, 1);
;   ATT_STORE(rkA, rvA, 0);
;   __syncthreads();
	v_lshrrev_b32_e32 v45, 1, v74
	v_mul_hi_i32 v27, v25, s26
	v_and_b32_e32 v44, 16, v44
	v_and_b32_e32 v45, 12, v45
	v_and_b32_e32 v51, 35, v74
	v_cvt_pk_bf16_f32 v4, v28, v29
	v_lshrrev_b32_e32 v28, 31, v27
	v_ashrrev_i32_e32 v27, 1, v27
	v_and_b32_e32 v50, 3, v74
	v_or3_b32 v44, v51, v44, v45
	v_add_u32_e32 v76, v27, v28
	v_lshlrev_b32_e32 v79, 7, v44
	v_bitop3_b32 v44, v45, v46, v50 bitop3:0x36
	v_lshlrev_b32_e32 v24, 3, v46
	v_mul_lo_u32 v27, v76, 12
	v_lshlrev_b32_e32 v80, 3, v44
	v_lshlrev_b32_e32 v44, 2, v75
	v_lshrrev_b32_e32 v45, 1, v75
	v_sub_u32_e32 v73, v25, v27
	v_mov_b64_e32 v[48:49], s[12:13]
	v_ashrrev_i32_e32 v25, 31, v24
	v_and_b32_e32 v44, 16, v44
	v_and_b32_e32 v45, 12, v45
	v_and_b32_e32 v50, 35, v75
	v_pk_mul_f32 v[34:35], v[34:35], s[6:7] op_sel_hi:[1,0]
	v_mad_i64_i32 v[28:29], s[12:13], v74, s25, v[48:49]
	v_lshlrev_b64 v[64:65], 1, v[24:25]
	v_and_b32_e32 v46, 3, v75
	v_or3_b32 v44, v50, v44, v45
	v_cvt_pk_bf16_f32 v10, v34, v35
	v_lshl_add_u64 v[24:25], v[28:29], 0, v[64:65]
	v_mad_i64_i32 v[28:29], s[12:13], v75, s25, v[48:49]
	v_mad_i64_i32 v[34:35], s[12:13], v76, s25, v[48:49]
	v_lshlrev_b32_e32 v81, 7, v44
	v_bitop3_b32 v44, v45, v47, v46 bitop3:0x36
	v_pk_mul_f32 v[32:33], v[32:33], s[6:7] op_sel_hi:[1,0]
	s_add_u32 s12, s66, s50
	v_lshlrev_b32_e32 v82, 3, v44
	v_lshlrev_b32_e32 v44, 2, v76
	v_lshlrev_b32_e32 v30, 16, v6
	v_and_b32_e32 v31, 0xffff0000, v6
	v_lshlrev_b32_e32 v6, 16, v7
	v_and_b32_e32 v7, 0xffff0000, v7
	v_cvt_pk_bf16_f32 v1, v36, v37
	v_cvt_pk_bf16_f32 v8, v32, v33
	v_lshlrev_b32_e32 v26, 3, v47
	v_lshlrev_b32_e32 v32, 3, v73
	s_addc_u32 s13, s67, s51
	v_lshlrev_b32_e32 v36, 4, v70
	v_and_b32_e32 v83, 16, v44
	v_lshrrev_b32_e32 v44, 1, v76
	v_pk_mul_f32 v[42:43], v[6:7], s[6:7] op_sel_hi:[1,0]
	v_ashrrev_i32_e32 v27, 31, v26
	v_ashrrev_i32_e32 v33, 31, v32
	v_and_b32_e32 v128, 0x70, v36
	v_and_b32_e32 v84, 12, v44
	v_add_u32_e32 v44, 64, v74
	v_add_u32_e32 v50, 64, v75
	v_add_u32_e32 v52, 64, v76
	v_mov_b64_e32 v[56:57], s[12:13]
	v_cvt_pk_bf16_f32 v7, v42, v43
	v_lshlrev_b64 v[66:67], 1, v[26:27]
	v_lshlrev_b64 v[68:69], 1, v[32:33]
	v_lshl_add_u64 v[42:43], s[12:13], 0, v[128:129]
	v_mad_i64_i32 v[44:45], s[68:69], v44, s25, v[48:49]
	v_mad_i64_i32 v[50:51], s[68:69], v50, s25, v[48:49]
	v_mad_i64_i32 v[48:49], s[68:69], v52, s25, v[48:49]
	v_mad_i64_i32 v[58:59], s[12:13], v77, s27, v[56:57]
	v_mad_i64_i32 v[56:57], s[12:13], v78, s27, v[56:57]
	v_pk_mul_f32 v[30:31], v[30:31], s[6:7] op_sel_hi:[1,0]
	v_lshl_add_u64 v[28:29], v[28:29], 0, v[66:67]
	v_lshl_add_u64 v[32:33], v[34:35], 0, v[68:69]
	v_mad_i64_i32 v[36:37], s[68:69], v77, s27, v[42:43]
	v_mad_i64_i32 v[40:41], s[68:69], v78, s27, v[42:43]
	v_lshl_add_u64 v[44:45], v[44:45], 0, v[64:65]
	v_lshl_add_u64 v[50:51], v[50:51], 0, v[66:67]
	v_lshl_add_u64 v[52:53], v[48:49], 0, v[68:69]
	v_lshl_add_u64 v[58:59], v[58:59], 0, v[128:129]
	v_lshl_add_u64 v[60:61], v[56:57], 0, v[128:129]
	v_cvt_pk_bf16_f32 v3, v38, v39
	v_cvt_pk_bf16_f32 v6, v30, v31
	global_load_dwordx4 v[24:27], v[24:25], off
	s_nop 0
	global_load_dwordx4 v[28:31], v[28:29], off
	v_and_b32_e32 v85, 3, v76
	global_load_dwordx4 v[32:35], v[32:33], off
	v_and_b32_e32 v86, 35, v76
	global_load_dwordx4 v[36:39], v[36:37], off
	v_or3_b32 v83, v86, v83, v84
	global_load_dwordx4 v[40:43], v[40:41], off
	v_bitop3_b32 v73, v84, v73, v85 bitop3:0x36
	global_load_dwordx4 v[44:47], v[44:45], off
	s_nop 0
	global_load_dwordx4 v[48:51], v[50:51], off
	s_nop 0
	global_load_dwordx4 v[52:55], v[52:53], off
	s_nop 0
	global_load_dwordx4 v[56:59], v[58:59], off offset:128
	s_nop 0
	global_load_dwordx4 v[60:63], v[60:61], off offset:128
	v_lshlrev_b32_e32 v83, 7, v83
	v_lshlrev_b32_e32 v73, 3, v73
	v_add_lshl_u32 v181, v83, v73, 1
	v_xor_b32_e32 v73, v77, v70
	v_lshlrev_b32_e32 v73, 4, v73
	v_and_b32_e32 v73, 0x70, v73
	v_add_lshl_u32 v179, v79, v80, 1
	v_lshl_or_b32 v182, v77, 7, v73
	v_xor_b32_e32 v73, v78, v70
	v_bitop3_b32 v79, v72, v71, 3 bitop3:0x6c
	v_lshlrev_b32_e32 v80, 8, v71
	v_lshlrev_b32_e32 v73, 4, v73
	v_lshl_or_b32 v184, v79, 4, v80
	v_bitop3_b32 v79, v178, v71, 4 bitop3:0x36
	v_and_b32_e32 v73, 0x70, v73
	v_lshl_or_b32 v185, v79, 4, v80
	v_and_b32_e32 v79, 7, v70
	v_lshl_or_b32 v183, v78, 7, v73
	v_lshlrev_b32_e32 v73, 7, v71
	v_bitop3_b32 v70, v72, v79, 3 bitop3:0x6c
	v_bitop3_b32 v71, v178, v71, 8 bitop3:0x36
	v_lshl_or_b32 v187, v70, 4, v73
	v_bitop3_b32 v70, v178, v79, 4 bitop3:0x36
	v_lshl_or_b32 v186, v71, 4, v80
	v_lshl_or_b32 v188, v70, 4, v73
	v_mov_b64_e32 v[70:71], s[4:5]
	v_mad_i64_i32 v[72:73], s[12:13], v77, s27, v[70:71]
	v_lshlrev_b32_e32 v128, 4, v79
	v_mad_i64_i32 v[70:71], s[12:13], v78, s27, v[70:71]
	v_lshl_add_u64 v[70:71], v[70:71], 0, v[128:129]
	v_lshl_add_u64 v[72:73], v[72:73], 0, v[128:129]
	v_lshl_add_u64 v[136:137], v[70:71], 0, s[50:51]
	v_mov_b64_e32 v[70:71], s[34:35]
	v_lshl_add_u64 v[134:135], v[72:73], 0, s[50:51]
	v_mad_i64_i32 v[72:73], s[12:13], v76, s25, v[70:71]
	v_mad_i64_i32 v[72:73], s[12:13], s0, v177, v[72:73]
	v_lshl_add_u64 v[138:139], v[72:73], 0, v[68:69]
	v_mad_i64_i32 v[68:69], s[12:13], v75, s25, v[70:71]
	v_mad_i64_i32 v[68:69], s[12:13], s0, v177, v[68:69]
	v_lshl_add_u64 v[140:141], v[68:69], 0, v[66:67]
	v_mad_i64_i32 v[66:67], s[12:13], v74, s25, v[70:71]
	v_mad_i64_i32 v[66:67], s[0:1], s0, v177, v[66:67]
	v_lshl_add_u64 v[142:143], v[66:67], 0, v[64:65]
	s_add_u32 s98, s60, 0x27030000
	s_addc_u32 s99, s61, 0
	v_lshl_add_u64 v[138:139], v[138:139], 0, s[98:99]
	v_lshl_add_u64 v[140:141], v[140:141], 0, s[98:99]
	v_lshl_add_u64 v[142:143], v[142:143], 0, s[98:99]
	s_add_u32 s98, s60, 0x30000000
	s_addc_u32 s99, s61, 0
	v_lshl_add_u64 v[134:135], v[134:135], 0, s[98:99]
	v_lshl_add_u64 v[136:137], v[136:137], 0, s[98:99]
	s_mov_b32 s98, 0x18000
	s_mov_b32 s99, 0
	v_mov_b32_e32 v66, v129
	v_mov_b32_e32 v67, v129
	v_add_lshl_u32 v180, v81, v82, 1
	v_mov_b32_e32 v128, v129
	v_mov_b32_e32 v64, v129
	v_mov_b32_e32 v65, v129
	v_mov_b64_e32 v[82:83], v[66:67]
	v_mov_b64_e32 v[70:71], v[66:67]
	v_mov_b64_e32 v[86:87], v[66:67]
	v_mov_b64_e32 v[74:75], v[66:67]
	v_mov_b64_e32 v[90:91], v[66:67]
	v_mov_b64_e32 v[78:79], v[66:67]
	v_mov_b64_e32 v[94:95], v[66:67]
	v_mov_b64_e32 v[80:81], v[64:65]
	v_mov_b64_e32 v[68:69], v[64:65]
	v_mov_b64_e32 v[84:85], v[64:65]
	v_mov_b64_e32 v[72:73], v[64:65]
	v_mov_b64_e32 v[88:89], v[64:65]
	v_mov_b64_e32 v[76:77], v[64:65]
	v_mov_b64_e32 v[92:93], v[64:65]
	v_mov_b64_e32 v[144:145], v[128:129]
	s_waitcnt vmcnt(9)
	ds_write_b128 v179, v[24:27]
	s_waitcnt vmcnt(8)
	ds_write_b128 v180, v[28:31]
	s_waitcnt vmcnt(7)
	ds_write_b128 v181, v[32:35]
	s_waitcnt vmcnt(6)
	ds_write_b128 v182, v[36:39] offset:16384
	s_waitcnt vmcnt(5)
	ds_write_b128 v183, v[40:43] offset:16384
	s_waitcnt lgkmcnt(0)
	s_barrier
	s_branch .LBB0_376

; #define MFMA16(a, b, c) __builtin_amdgcn_mfma_f32_16x16x32_bf16((a), (b), (c), 0, 0, 0)
; static __device__ __forceinline__ void attn_item(const Params& p, int head, int j, char* smraw) {
;     ...
;     f32x4 sacc[4][2];
; #pragma unroll
;     for (int b = 0; b < 2; ++b) {
;       const float mi = -mrun[b];
; #pragma unroll
;       for (int a = 0; a < 4; ++a) sacc[a][b] = f32x4{mi, mi, mi, mi};
;     }
;     {
;       bf16x8 kf[3][4];
; #pragma unroll
;       for (int ks = 0; ks < 3; ++ks)
; #pragma unroll
;         for (int kt = 0; kt < 4; ++kt) kf[ks][kt] = *(const bf16x8*)(cK + (kt * 16 + l15) * 128 + (((ks * 4 + quad) ^ l15) << 3));
;       __builtin_amdgcn_sched_barrier(0);
;       __builtin_amdgcn_s_setprio(1);
; #pragma unroll
;       for (int ks = 0; ks < 3; ++ks)
; #pragma unroll
;         for (int kt = 0; kt < 4; ++kt)
; #pragma unroll
;           for (int qt = 0; qt < 2; ++qt) sacc[kt][qt] = MFMA16(kf[ks][kt], qf[qt][ks], sacc[kt][qt]);
;       __builtin_amdgcn_s_setprio(0);
;       __builtin_amdgcn_sched_barrier(0);
;     }
;     float mx[2];
; #pragma unroll
;     for (int qt = 0; qt < 2; ++qt) {
;       float m = sacc[0][qt][0];
; #pragma unroll
;       for (int kt = 0; kt < 4; ++kt)
; #pragma unroll
;         for (int r = 0; r < 4; ++r) m = fmaxf(m, sacc[kt][qt][r]);
;       mx[qt] = max_x16_x32(m);
;     }
;     if (__any(first || mx[0] > THR || mx[1] > THR)) {
; #pragma unroll
;       for (int qt = 0; qt < 2; ++qt) {
;         const float d = first ? mx[qt] : fmaxf(mx[qt], 0.f);
;         const float alpha = first ? 1.f : __builtin_amdgcn_exp2f(-d);
;         mrun[qt] += d;
;         lrun[qt] *= alpha;
; #pragma unroll
;         for (int dt = 0; dt < 4; ++dt) oacc[dt][qt] = oacc[dt][qt] * alpha;
; #pragma unroll
;         for (int kt = 0; kt < 4; ++kt)
; #pragma unroll
;           for (int r = 0; r < 4; ++r) sacc[kt][qt][r] -= d;
;       }
.LBB0_378:
	ds_read_b128 v[100:103], v184
	ds_read_b128 v[104:107], v184 offset:4096
	ds_read_b128 v[108:111], v184 offset:8192
	ds_read_b128 v[112:115], v184 offset:12288
	ds_read_b128 v[116:119], v185
	ds_read_b128 v[120:123], v185 offset:4096
	ds_read_b128 v[124:127], v185 offset:8192
	ds_read_b128 v[156:159], v185 offset:12288
	ds_read_b128 v[160:163], v186
	ds_read_b128 v[164:167], v186 offset:4096
	ds_read_b128 v[168:171], v186 offset:8192
	ds_read_b128 v[192:195], v186 offset:12288
	s_cmp_eq_u32 s3, 3
	s_cselect_b64 s[0:1], -1, 0
	s_setprio 1
	s_waitcnt lgkmcnt(11)
	v_mfma_f32_16x16x32_bf16 v[200:203], v[100:103], v[0:3], v[232:235]
	v_mfma_f32_16x16x32_bf16 v[100:103], v[100:103], v[12:15], v[236:239]
	s_waitcnt lgkmcnt(10)
	v_mfma_f32_16x16x32_bf16 v[204:207], v[104:107], v[0:3], v[232:235]
	v_mfma_f32_16x16x32_bf16 v[104:107], v[104:107], v[12:15], v[236:239]
	s_waitcnt lgkmcnt(9)
	v_mfma_f32_16x16x32_bf16 v[208:211], v[108:111], v[0:3], v[232:235]
	v_mfma_f32_16x16x32_bf16 v[108:111], v[108:111], v[12:15], v[236:239]
	s_waitcnt lgkmcnt(8)
	v_mfma_f32_16x16x32_bf16 v[96:99], v[112:115], v[0:3], v[232:235]
	v_mfma_f32_16x16x32_bf16 v[112:115], v[112:115], v[12:15], v[236:239]
	s_waitcnt lgkmcnt(7)
	v_mfma_f32_16x16x32_bf16 v[196:199], v[116:119], v[4:7], v[200:203]
	v_mfma_f32_16x16x32_bf16 v[100:103], v[116:119], v[16:19], v[100:103]
	s_waitcnt lgkmcnt(6)
	v_mfma_f32_16x16x32_bf16 v[116:119], v[120:123], v[4:7], v[204:207]
	v_mfma_f32_16x16x32_bf16 v[104:107], v[120:123], v[16:19], v[104:107]
	s_waitcnt lgkmcnt(5)
	v_mfma_f32_16x16x32_bf16 v[200:203], v[124:127], v[4:7], v[208:211]
	v_mfma_f32_16x16x32_bf16 v[204:207], v[124:127], v[16:19], v[108:111]
	s_waitcnt lgkmcnt(4)
	v_mfma_f32_16x16x32_bf16 v[96:99], v[156:159], v[4:7], v[96:99]
	v_mfma_f32_16x16x32_bf16 v[156:159], v[156:159], v[16:19], v[112:115]
	s_waitcnt lgkmcnt(3)
	v_mfma_f32_16x16x32_bf16 v[124:127], v[160:163], v[8:11], v[196:199]
	v_mfma_f32_16x16x32_bf16 v[108:111], v[160:163], v[20:23], v[100:103]
	s_waitcnt lgkmcnt(2)
	v_mfma_f32_16x16x32_bf16 v[120:123], v[164:167], v[8:11], v[116:119]
	v_mfma_f32_16x16x32_bf16 v[104:107], v[164:167], v[20:23], v[104:107]
	s_waitcnt lgkmcnt(1)
	v_mfma_f32_16x16x32_bf16 v[116:119], v[168:171], v[8:11], v[200:203]
	v_mfma_f32_16x16x32_bf16 v[100:103], v[168:171], v[20:23], v[204:207]
	s_waitcnt lgkmcnt(0)
	v_mfma_f32_16x16x32_bf16 v[112:115], v[192:195], v[8:11], v[96:99]
	v_mfma_f32_16x16x32_bf16 v[96:99], v[192:195], v[20:23], v[156:159]
	s_setprio 0
	v_max3_f32 v128, v124, v125, v126
	v_max3_f32 v128, v128, v127, v120
	v_max3_f32 v156, v108, v109, v110
	v_max3_f32 v128, v128, v121, v122
	v_max3_f32 v156, v156, v111, v104
	v_max3_f32 v128, v128, v123, v116
	v_max3_f32 v156, v156, v105, v106
	v_max3_f32 v128, v128, v117, v118
	v_max3_f32 v156, v156, v107, v100
	v_max3_f32 v128, v128, v119, v112
	v_max3_f32 v156, v156, v101, v102
	v_max3_f32 v128, v128, v113, v114
	v_max3_f32 v156, v156, v103, v96
	v_max_f32_e32 v128, v128, v115
	v_max3_f32 v156, v156, v97, v98
	v_max_f32_e32 v156, v156, v99
	v_max_f32_e32 v157, v128, v156
	v_cmp_lt_f32_e32 vcc, s33, v157
	s_or_b64 vcc, s[0:1], vcc
	s_cbranch_vccz .LBB0_380
	v_mov_b32_e32 v157, v128
	s_nop 1
	v_permlane16_swap_b32_e32 v128, v157
	v_max_f32_e32 v157, v157, v157
	v_max_f32_e32 v128, v128, v128
	v_max_f32_e32 v128, v128, v157
	v_mov_b32_e32 v157, v128
	s_nop 1
	v_permlane32_swap_b32_e32 v128, v157
	v_max_f32_e32 v157, v157, v157
	v_max_f32_e32 v128, v128, v128
	v_max_f32_e32 v128, v128, v157
	v_mov_b32_e32 v157, v156
	s_nop 1
	v_permlane16_swap_b32_e32 v156, v157
	v_max_f32_e32 v157, v157, v157
	v_max_f32_e32 v156, v156, v156
	v_max_f32_e32 v156, v156, v157
	v_mov_b32_e32 v157, v156
	s_nop 1
	v_permlane32_swap_b32_e32 v156, v157
	v_max_f32_e32 v157, v157, v157
	v_max_f32_e32 v156, v156, v156
	v_max_f32_e32 v156, v156, v157
	v_max_f32_e32 v157, v128, v128
	v_max_f32_e32 v157, 0, v157
	v_max_f32_e32 v158, v156, v156
	v_cndmask_b32_e64 v128, v157, v128, s[0:1]
	v_max_f32_e32 v158, 0, v158
	v_exp_f32_e64 v157, -v128
	v_cndmask_b32_e64 v156, v158, v156, s[0:1]
	v_exp_f32_e64 v158, -v156
	v_add_f32_e32 v190, v190, v128
	v_xor_b32_e32 v232, 0x80000000, v190
	v_mov_b32_e32 v233, v232
	v_mov_b32_e32 v234, v232
	v_mov_b32_e32 v235, v232
	v_cndmask_b32_e64 v159, v157, 1.0, s[0:1]
	v_pk_add_f32 v[124:125], v[124:125], v[128:129] op_sel_hi:[1,0] neg_lo:[0,1] neg_hi:[0,1]
	v_pk_add_f32 v[126:127], v[126:127], v[128:129] op_sel_hi:[1,0] neg_lo:[0,1] neg_hi:[0,1]
	v_pk_add_f32 v[120:121], v[120:121], v[128:129] op_sel_hi:[1,0] neg_lo:[0,1] neg_hi:[0,1]
	v_pk_add_f32 v[122:123], v[122:123], v[128:129] op_sel_hi:[1,0] neg_lo:[0,1] neg_hi:[0,1]
	v_pk_add_f32 v[116:117], v[116:117], v[128:129] op_sel_hi:[1,0] neg_lo:[0,1] neg_hi:[0,1]
	v_pk_add_f32 v[118:119], v[118:119], v[128:129] op_sel_hi:[1,0] neg_lo:[0,1] neg_hi:[0,1]
	v_pk_add_f32 v[112:113], v[112:113], v[128:129] op_sel_hi:[1,0] neg_lo:[0,1] neg_hi:[0,1]
	v_pk_add_f32 v[114:115], v[114:115], v[128:129] op_sel_hi:[1,0] neg_lo:[0,1] neg_hi:[0,1]
	v_cndmask_b32_e64 v158, v158, 1.0, s[0:1]
	v_mov_b32_e32 v128, v159
	v_pk_mul_f32 v[94:95], v[94:95], v[128:129] op_sel_hi:[1,0]
	v_pk_mul_f32 v[92:93], v[92:93], v[128:129] op_sel_hi:[1,0]
	v_pk_mul_f32 v[90:91], v[90:91], v[128:129] op_sel_hi:[1,0]
	v_pk_mul_f32 v[88:89], v[88:89], v[128:129] op_sel_hi:[1,0]
	v_pk_mul_f32 v[86:87], v[86:87], v[128:129] op_sel_hi:[1,0]
	v_pk_mul_f32 v[84:85], v[84:85], v[128:129] op_sel_hi:[1,0]
	v_pk_mul_f32 v[82:83], v[82:83], v[128:129] op_sel_hi:[1,0]
	v_pk_mul_f32 v[80:81], v[80:81], v[128:129] op_sel_hi:[1,0]
	v_add_f32_e32 v189, v189, v156
	v_xor_b32_e32 v236, 0x80000000, v189
	v_mov_b32_e32 v237, v236
	v_mov_b32_e32 v238, v236
	v_mov_b32_e32 v239, v236
	v_pk_mul_f32 v[144:145], v[144:145], v[158:159]
	v_pk_mul_f32 v[78:79], v[78:79], v[158:159] op_sel_hi:[1,0]
	v_pk_mul_f32 v[76:77], v[76:77], v[158:159] op_sel_hi:[1,0]
	v_pk_mul_f32 v[74:75], v[74:75], v[158:159] op_sel_hi:[1,0]
	v_pk_mul_f32 v[72:73], v[72:73], v[158:159] op_sel_hi:[1,0]
	v_pk_mul_f32 v[70:71], v[70:71], v[158:159] op_sel_hi:[1,0]
	v_pk_mul_f32 v[68:69], v[68:69], v[158:159] op_sel_hi:[1,0]
	v_pk_mul_f32 v[66:67], v[66:67], v[158:159] op_sel_hi:[1,0]
	v_pk_mul_f32 v[64:65], v[64:65], v[158:159] op_sel_hi:[1,0]
	v_pk_add_f32 v[108:109], v[108:109], v[156:157] op_sel_hi:[1,0] neg_lo:[0,1] neg_hi:[0,1]
	v_pk_add_f32 v[110:111], v[110:111], v[156:157] op_sel_hi:[1,0] neg_lo:[0,1] neg_hi:[0,1]
	v_pk_add_f32 v[104:105], v[104:105], v[156:157] op_sel_hi:[1,0] neg_lo:[0,1] neg_hi:[0,1]
	v_pk_add_f32 v[106:107], v[106:107], v[156:157] op_sel_hi:[1,0] neg_lo:[0,1] neg_hi:[0,1]
	v_pk_add_f32 v[100:101], v[100:101], v[156:157] op_sel_hi:[1,0] neg_lo:[0,1] neg_hi:[0,1]
	v_pk_add_f32 v[102:103], v[102:103], v[156:157] op_sel_hi:[1,0] neg_lo:[0,1] neg_hi:[0,1]
	v_pk_add_f32 v[96:97], v[96:97], v[156:157] op_sel_hi:[1,0] neg_lo:[0,1] neg_hi:[0,1]
	v_pk_add_f32 v[98:99], v[98:99], v[156:157] op_sel_hi:[1,0] neg_lo:[0,1] neg_hi:[0,1]
; #define MFMA16(a, b, c) __builtin_amdgcn_mfma_f32_16x16x32_bf16((a), (b), (c), 0, 0, 0)
; static __device__ __forceinline__ void attn_item(const Params& p, int head, int j, char* smraw) {
;     ...
;     bf16x8 pf[2][2];
; #pragma unroll
;     for (int qt = 0; qt < 2; ++qt) {
;       float ps = 0.f;
; #pragma unroll
;       for (int kt = 0; kt < 4; ++kt)
; #pragma unroll
;         for (int r = 0; r < 4; ++r) {
;           const float pv = __builtin_amdgcn_exp2f(sacc[kt][qt][r]);
;           sacc[kt][qt][r] = pv; ps += pv;
;         }
;       lrun[qt] += ps;
; #pragma unroll
;       for (int k2 = 0; k2 < 2; ++k2) {
;         u32x4 pk = {cvtpk(sacc[2 * k2][qt][0], sacc[2 * k2][qt][1]), cvtpk(sacc[2 * k2][qt][2], sacc[2 * k2][qt][3]),
;                     cvtpk(sacc[2 * k2 + 1][qt][0], sacc[2 * k2 + 1][qt][1]), cvtpk(sacc[2 * k2 + 1][qt][2], sacc[2 * k2 + 1][qt][3])};
;         pf[qt][k2] = *(bf16x8*)&pk;
;       }
;     }
;     {
;       bf16x8 vf[2][4];
; #pragma unroll
;       for (int k2 = 0; k2 < 2; ++k2)
; #pragma unroll
;         for (int dt = 0; dt < 4; ++dt) vf[k2][dt] = *(const bf16x8*)(cV + (dt * 16 + l15) * 64 + (((k2 * 4 + quad) ^ (l15 & 7)) << 3));
;       __builtin_amdgcn_sched_barrier(0);
;       __builtin_amdgcn_s_setprio(1);
; #pragma unroll
;       for (int k2 = 0; k2 < 2; ++k2)
; #pragma unroll
;         for (int dt = 0; dt < 4; ++dt)
; #pragma unroll
;           for (int qt = 0; qt < 2; ++qt) oacc[dt][qt] = MFMA16(vf[k2][dt], pf[qt][k2], oacc[dt][qt]);
;       __builtin_amdgcn_s_setprio(0);
;       __builtin_amdgcn_sched_barrier(0);
;     }
;     ...
;     ATT_STORE(rkB, rvB, 1);
;     __syncthreads();
;     if (t + 3 < NT) ATT_LOAD(rkB, rvB, t + 3);
.LBB0_380:
	v_exp_f32_e32 v173, v124
	v_exp_f32_e32 v169, v126
	v_exp_f32_e32 v161, v122
	v_exp_f32_e32 v172, v108
	v_exp_f32_e32 v170, v109
	v_exp_f32_e32 v168, v110
	v_exp_f32_e32 v166, v111
	v_exp_f32_e32 v164, v104
	v_exp_f32_e32 v162, v105
	v_exp_f32_e32 v160, v106
	v_exp_f32_e32 v158, v107
	v_exp_f32_e32 v156, v100
	v_exp_f32_e32 v126, v101
	v_exp_f32_e32 v124, v102
	v_exp_f32_e32 v122, v103
	ds_read_b128 v[100:103], v187 offset:16384
	ds_read_b128 v[104:107], v187 offset:18432
	ds_read_b128 v[108:111], v187 offset:20480
	ds_read_b128 v[200:203], v187 offset:22528
	ds_read_b128 v[204:207], v188 offset:16384
	ds_read_b128 v[208:211], v188 offset:18432
	ds_read_b128 v[212:215], v188 offset:20480
	ds_read_b128 v[216:219], v188 offset:22528
	v_exp_f32_e32 v171, v125
	v_exp_f32_e32 v167, v127
	v_exp_f32_e32 v165, v120
	v_exp_f32_e32 v163, v121
	v_exp_f32_e32 v159, v123
	v_exp_f32_e32 v157, v116
	v_exp_f32_e32 v127, v117
	v_exp_f32_e32 v125, v118
	v_exp_f32_e32 v123, v119
	v_exp_f32_e32 v121, v112
	v_exp_f32_e32 v119, v113
	v_exp_f32_e32 v117, v114
	v_exp_f32_e32 v113, v115
	v_exp_f32_e32 v120, v96
	v_exp_f32_e32 v118, v97
	v_exp_f32_e32 v116, v98
	v_exp_f32_e32 v112, v99
	v_cvt_pk_bf16_f32 v192, v173, v171
	v_cvt_pk_bf16_f32 v193, v169, v167
	v_cvt_pk_bf16_f32 v194, v165, v163
	v_cvt_pk_bf16_f32 v195, v161, v159
	v_cvt_pk_bf16_f32 v196, v157, v127
	v_cvt_pk_bf16_f32 v197, v125, v123
	v_cvt_pk_bf16_f32 v198, v121, v119
	v_cvt_pk_bf16_f32 v199, v117, v113
	v_cvt_pk_bf16_f32 v96, v172, v170
	v_cvt_pk_bf16_f32 v97, v168, v166
	v_cvt_pk_bf16_f32 v98, v164, v162
	v_cvt_pk_bf16_f32 v99, v160, v158
	v_cvt_pk_bf16_f32 v220, v156, v126
	v_cvt_pk_bf16_f32 v221, v124, v122
	v_cvt_pk_bf16_f32 v222, v120, v118
	v_cvt_pk_bf16_f32 v223, v116, v112
	s_setprio 1
	s_waitcnt lgkmcnt(7)
	v_mfma_f32_16x16x32_bf16 v[92:95], v[100:103], v[192:195], v[92:95]
	v_mfma_f32_16x16x32_bf16 v[76:79], v[100:103], v[96:99], v[76:79]
	v_add_f32_e32 v226, v170, v172
	v_add_f32_e32 v227, v171, v173
	s_waitcnt lgkmcnt(6)
	v_mfma_f32_16x16x32_bf16 v[100:103], v[104:107], v[192:195], v[88:91]
	v_add_f32_e32 v226, v168, v226
	v_add_f32_e32 v227, v169, v227
	v_mfma_f32_16x16x32_bf16 v[72:75], v[104:107], v[96:99], v[72:75]
	v_add_f32_e32 v226, v166, v226
	v_add_f32_e32 v227, v167, v227
	s_waitcnt lgkmcnt(5)
	v_mfma_f32_16x16x32_bf16 v[104:107], v[108:111], v[192:195], v[84:87]
	v_add_f32_e32 v226, v164, v226
	v_add_f32_e32 v227, v165, v227
	v_mfma_f32_16x16x32_bf16 v[68:71], v[108:111], v[96:99], v[68:71]
	v_add_f32_e32 v226, v162, v226
	v_add_f32_e32 v227, v163, v227
	s_waitcnt lgkmcnt(4)
	v_mfma_f32_16x16x32_bf16 v[108:111], v[200:203], v[192:195], v[80:83]
	v_add_f32_e32 v226, v160, v226
	v_add_f32_e32 v227, v161, v227
	v_mfma_f32_16x16x32_bf16 v[64:67], v[200:203], v[96:99], v[64:67]
	v_add_f32_e32 v226, v158, v226
	v_add_f32_e32 v227, v159, v227
	s_waitcnt lgkmcnt(3)
	v_mfma_f32_16x16x32_bf16 v[92:95], v[204:207], v[196:199], v[92:95]
	v_add_f32_e32 v226, v156, v226
	v_add_f32_e32 v227, v157, v227
	v_mfma_f32_16x16x32_bf16 v[88:91], v[204:207], v[220:223], v[76:79]
	v_add_f32_e32 v226, v126, v226
	v_add_f32_e32 v227, v127, v227
	s_waitcnt lgkmcnt(2)
	v_mfma_f32_16x16x32_bf16 v[84:87], v[208:211], v[196:199], v[100:103]
	v_add_f32_e32 v226, v124, v226
	v_add_f32_e32 v227, v125, v227
	v_mfma_f32_16x16x32_bf16 v[80:83], v[208:211], v[220:223], v[72:75]
	v_add_f32_e32 v226, v122, v226
	v_add_f32_e32 v227, v123, v227
	s_waitcnt lgkmcnt(1)
	v_mfma_f32_16x16x32_bf16 v[76:79], v[212:215], v[196:199], v[104:107]
	v_add_f32_e32 v226, v120, v226
	v_add_f32_e32 v227, v121, v227
	v_mfma_f32_16x16x32_bf16 v[72:75], v[212:215], v[220:223], v[68:71]
	v_add_f32_e32 v226, v118, v226
	v_add_f32_e32 v227, v119, v227
	s_waitcnt lgkmcnt(0)
	v_mfma_f32_16x16x32_bf16 v[68:71], v[216:219], v[196:199], v[108:111]
	v_add_f32_e32 v226, v116, v226
	v_add_f32_e32 v227, v117, v227
	v_mfma_f32_16x16x32_bf16 v[64:67], v[216:219], v[220:223], v[64:67]
	v_add_f32_e32 v226, v112, v226
	v_add_f32_e32 v227, v113, v227
	s_setprio 0
	v_pk_add_f32 v[144:145], v[144:145], v[226:227]
	s_cmp_ge_u32 s3, s2
	s_waitcnt vmcnt(4)
	ds_write_b128 v179, v[44:47] offset:24576
	s_waitcnt vmcnt(3)
	ds_write_b128 v180, v[48:51] offset:24576
	s_waitcnt vmcnt(2)
	ds_write_b128 v181, v[52:55] offset:24576
	s_waitcnt vmcnt(1)
	ds_write_b128 v182, v[56:59] offset:40960
	s_waitcnt vmcnt(0)
	ds_write_b128 v183, v[60:63] offset:40960
	s_waitcnt lgkmcnt(0)
	s_barrier
	s_cbranch_scc1 .LBB0_382
	v_lshl_add_u64 v[44:45], v[142:143], 0, s[98:99]
	v_lshl_add_u64 v[48:49], v[140:141], 0, s[98:99]
	v_lshl_add_u64 v[52:53], v[138:139], 0, s[98:99]
	global_load_dwordx4 v[44:47], v[44:45], off
	s_nop 0
	global_load_dwordx4 v[48:51], v[48:49], off
	s_nop 0
	global_load_dwordx4 v[52:55], v[52:53], off
	global_load_dwordx4 v[56:59], v[134:135], off offset:384
	global_load_dwordx4 v[60:63], v[136:137], off offset:384
; #define MFMA16(a, b, c) __builtin_amdgcn_mfma_f32_16x16x32_bf16((a), (b), (c), 0, 0, 0)
; static __device__ __forceinline__ void attn_item(const Params& p, int head, int j, char* smraw) {
;     ...
;     f32x4 sacc[4][2];
; #pragma unroll
;     for (int b = 0; b < 2; ++b) {
;       const float mi = -mrun[b];
; #pragma unroll
;       for (int a = 0; a < 4; ++a) sacc[a][b] = f32x4{mi, mi, mi, mi};
;     }
;     {
;       bf16x8 kf[3][4];
; #pragma unroll
;       for (int ks = 0; ks < 3; ++ks)
; #pragma unroll
;         for (int kt = 0; kt < 4; ++kt) kf[ks][kt] = *(const bf16x8*)(cK + (kt * 16 + l15) * 128 + (((ks * 4 + quad) ^ l15) << 3));
;       __builtin_amdgcn_sched_barrier(0);
;       __builtin_amdgcn_s_setprio(1);
; #pragma unroll
;       for (int ks = 0; ks < 3; ++ks)
; #pragma unroll
;         for (int kt = 0; kt < 4; ++kt)
; #pragma unroll
;           for (int qt = 0; qt < 2; ++qt) sacc[kt][qt] = MFMA16(kf[ks][kt], qf[qt][ks], sacc[kt][qt]);
;       __builtin_amdgcn_s_setprio(0);
;       __builtin_amdgcn_sched_barrier(0);
;     }
;     float mx[2];
; #pragma unroll
;     for (int qt = 0; qt < 2; ++qt) {
;       float m = sacc[0][qt][0];
; #pragma unroll
;       for (int kt = 0; kt < 4; ++kt)
; #pragma unroll
;         for (int r = 0; r < 4; ++r) m = fmaxf(m, sacc[kt][qt][r]);
;       mx[qt] = max_x16_x32(m);
;     }
;     if (__any(first || mx[0] > THR || mx[1] > THR)) {
; #pragma unroll
;       for (int qt = 0; qt < 2; ++qt) {
;         const float d = first ? mx[qt] : fmaxf(mx[qt], 0.f);
;         const float alpha = first ? 1.f : __builtin_amdgcn_exp2f(-d);
;         mrun[qt] += d;
;         lrun[qt] *= alpha;
; #pragma unroll
;         for (int dt = 0; dt < 4; ++dt) oacc[dt][qt] = oacc[dt][qt] * alpha;
; #pragma unroll
;         for (int kt = 0; kt < 4; ++kt)
; #pragma unroll
;           for (int r = 0; r < 4; ++r) sacc[kt][qt][r] -= d;
;       }
.LBB0_382:
	ds_read_b128 v[100:103], v184 offset:24576
	ds_read_b128 v[104:107], v184 offset:28672
	ds_read_b128 v[108:111], v184 offset:32768
	ds_read_b128 v[112:115], v184 offset:36864
	ds_read_b128 v[116:119], v185 offset:24576
	ds_read_b128 v[120:123], v185 offset:28672
	ds_read_b128 v[124:127], v185 offset:32768
	ds_read_b128 v[146:149], v185 offset:36864
	ds_read_b128 v[150:153], v186 offset:24576
	ds_read_b128 v[154:157], v186 offset:28672
	ds_read_b128 v[158:161], v186 offset:32768
	ds_read_b128 v[162:165], v186 offset:36864
	s_setprio 1
	s_waitcnt lgkmcnt(11)
	v_mfma_f32_16x16x32_bf16 v[170:173], v[100:103], v[0:3], v[232:235]
	v_mfma_f32_16x16x32_bf16 v[100:103], v[100:103], v[12:15], v[236:239]
	s_waitcnt lgkmcnt(10)
	v_mfma_f32_16x16x32_bf16 v[192:195], v[104:107], v[0:3], v[232:235]
	v_mfma_f32_16x16x32_bf16 v[104:107], v[104:107], v[12:15], v[236:239]
	s_waitcnt lgkmcnt(9)
	v_mfma_f32_16x16x32_bf16 v[196:199], v[108:111], v[0:3], v[232:235]
	v_mfma_f32_16x16x32_bf16 v[108:111], v[108:111], v[12:15], v[236:239]
	s_waitcnt lgkmcnt(8)
	v_mfma_f32_16x16x32_bf16 v[96:99], v[112:115], v[0:3], v[232:235]
	v_mfma_f32_16x16x32_bf16 v[112:115], v[112:115], v[12:15], v[236:239]
	s_waitcnt lgkmcnt(7)
	v_mfma_f32_16x16x32_bf16 v[166:169], v[116:119], v[4:7], v[170:173]
	v_mfma_f32_16x16x32_bf16 v[100:103], v[116:119], v[16:19], v[100:103]
	s_waitcnt lgkmcnt(6)
	v_mfma_f32_16x16x32_bf16 v[116:119], v[120:123], v[4:7], v[192:195]
	v_mfma_f32_16x16x32_bf16 v[104:107], v[120:123], v[16:19], v[104:107]
	s_waitcnt lgkmcnt(5)
	v_mfma_f32_16x16x32_bf16 v[170:173], v[124:127], v[4:7], v[196:199]
	v_mfma_f32_16x16x32_bf16 v[192:195], v[124:127], v[16:19], v[108:111]
	s_waitcnt lgkmcnt(4)
	v_mfma_f32_16x16x32_bf16 v[96:99], v[146:149], v[4:7], v[96:99]
	v_mfma_f32_16x16x32_bf16 v[146:149], v[146:149], v[16:19], v[112:115]
	s_waitcnt lgkmcnt(3)
	v_mfma_f32_16x16x32_bf16 v[124:127], v[150:153], v[8:11], v[166:169]
	v_mfma_f32_16x16x32_bf16 v[108:111], v[150:153], v[20:23], v[100:103]
	s_waitcnt lgkmcnt(2)
	v_mfma_f32_16x16x32_bf16 v[120:123], v[154:157], v[8:11], v[116:119]
	v_mfma_f32_16x16x32_bf16 v[104:107], v[154:157], v[20:23], v[104:107]
	s_waitcnt lgkmcnt(1)
	v_mfma_f32_16x16x32_bf16 v[116:119], v[158:161], v[8:11], v[170:173]
	v_mfma_f32_16x16x32_bf16 v[100:103], v[158:161], v[20:23], v[192:195]
	s_waitcnt lgkmcnt(0)
	v_mfma_f32_16x16x32_bf16 v[112:115], v[162:165], v[8:11], v[96:99]
	v_mfma_f32_16x16x32_bf16 v[96:99], v[162:165], v[20:23], v[146:149]
	s_setprio 0
	v_max3_f32 v128, v108, v109, v110
	v_max3_f32 v128, v128, v111, v104
	v_max3_f32 v146, v124, v125, v126
	v_max3_f32 v128, v128, v105, v106
	v_max3_f32 v146, v146, v127, v120
	v_max3_f32 v128, v128, v107, v100
	v_max3_f32 v146, v146, v121, v122
	v_max3_f32 v128, v128, v101, v102
	v_max3_f32 v146, v146, v123, v116
	v_max3_f32 v128, v128, v103, v96
	v_max3_f32 v146, v146, v117, v118
	v_max3_f32 v128, v128, v97, v98
	v_max3_f32 v146, v146, v119, v112
	v_max_f32_e32 v128, v128, v99
	v_max3_f32 v146, v146, v113, v114
	v_max_f32_e32 v146, v146, v115
	v_max_f32_e32 v147, v146, v128
	v_cmp_lt_f32_e32 vcc, s33, v147
	s_cbranch_vccz .LBB0_384
	v_mov_b32_e32 v147, v146
	s_nop 1
	v_permlane16_swap_b32_e32 v146, v147
	v_max_f32_e32 v147, v147, v147
	v_max_f32_e32 v146, v146, v146
	v_max_f32_e32 v146, v146, v147
	v_mov_b32_e32 v147, v146
	s_nop 1
	v_permlane32_swap_b32_e32 v146, v147
	v_max_f32_e32 v147, v147, v147
	v_max_f32_e32 v146, v146, v146
	v_max_f32_e32 v146, v146, v147
	v_mov_b32_e32 v147, v128
	s_nop 1
	v_permlane16_swap_b32_e32 v128, v147
	v_max_f32_e32 v147, v147, v147
	v_max_f32_e32 v128, v128, v128
	v_max_f32_e32 v128, v128, v147
	v_mov_b32_e32 v147, v128
	s_nop 1
	v_permlane32_swap_b32_e32 v128, v147
	v_max_f32_e32 v147, v147, v147
	v_max_f32_e32 v128, v128, v128
	v_max_f32_e32 v128, v128, v147
	v_max_f32_e32 v146, v146, v146
	v_max_f32_e32 v146, 0, v146
	v_max_f32_e32 v128, v128, v128
	v_exp_f32_e64 v148, -v146
	v_max_f32_e32 v128, 0, v128
	v_exp_f32_e64 v150, -v128
	v_add_f32_e32 v190, v190, v146
	v_xor_b32_e32 v232, 0x80000000, v190
	v_mov_b32_e32 v233, v232
	v_mov_b32_e32 v234, v232
	v_mov_b32_e32 v235, v232
	v_mov_b32_e32 v151, v148
	v_pk_mul_f32 v[94:95], v[94:95], v[148:149] op_sel_hi:[1,0]
	v_pk_mul_f32 v[92:93], v[92:93], v[148:149] op_sel_hi:[1,0]
	v_pk_mul_f32 v[86:87], v[86:87], v[148:149] op_sel_hi:[1,0]
	v_pk_mul_f32 v[84:85], v[84:85], v[148:149] op_sel_hi:[1,0]
	v_pk_mul_f32 v[78:79], v[78:79], v[148:149] op_sel_hi:[1,0]
	v_pk_mul_f32 v[76:77], v[76:77], v[148:149] op_sel_hi:[1,0]
	v_pk_mul_f32 v[70:71], v[70:71], v[148:149] op_sel_hi:[1,0]
	v_pk_mul_f32 v[68:69], v[68:69], v[148:149] op_sel_hi:[1,0]
	v_pk_add_f32 v[124:125], v[124:125], v[146:147] op_sel_hi:[1,0] neg_lo:[0,1] neg_hi:[0,1]
	v_pk_add_f32 v[126:127], v[126:127], v[146:147] op_sel_hi:[1,0] neg_lo:[0,1] neg_hi:[0,1]
	v_pk_add_f32 v[120:121], v[120:121], v[146:147] op_sel_hi:[1,0] neg_lo:[0,1] neg_hi:[0,1]
	v_pk_add_f32 v[122:123], v[122:123], v[146:147] op_sel_hi:[1,0] neg_lo:[0,1] neg_hi:[0,1]
	v_pk_add_f32 v[116:117], v[116:117], v[146:147] op_sel_hi:[1,0] neg_lo:[0,1] neg_hi:[0,1]
	v_pk_add_f32 v[118:119], v[118:119], v[146:147] op_sel_hi:[1,0] neg_lo:[0,1] neg_hi:[0,1]
	v_pk_add_f32 v[112:113], v[112:113], v[146:147] op_sel_hi:[1,0] neg_lo:[0,1] neg_hi:[0,1]
	v_pk_add_f32 v[114:115], v[114:115], v[146:147] op_sel_hi:[1,0] neg_lo:[0,1] neg_hi:[0,1]
	v_add_f32_e32 v189, v189, v128
	v_xor_b32_e32 v236, 0x80000000, v189
	v_mov_b32_e32 v237, v236
	v_mov_b32_e32 v238, v236
	v_mov_b32_e32 v239, v236
	v_pk_mul_f32 v[144:145], v[144:145], v[150:151]
	v_pk_mul_f32 v[90:91], v[90:91], v[150:151] op_sel_hi:[1,0]
	v_pk_mul_f32 v[88:89], v[88:89], v[150:151] op_sel_hi:[1,0]
	v_pk_mul_f32 v[82:83], v[82:83], v[150:151] op_sel_hi:[1,0]
	v_pk_mul_f32 v[80:81], v[80:81], v[150:151] op_sel_hi:[1,0]
	v_pk_mul_f32 v[74:75], v[74:75], v[150:151] op_sel_hi:[1,0]
	v_pk_mul_f32 v[72:73], v[72:73], v[150:151] op_sel_hi:[1,0]
	v_pk_mul_f32 v[66:67], v[66:67], v[150:151] op_sel_hi:[1,0]
	v_pk_mul_f32 v[64:65], v[64:65], v[150:151] op_sel_hi:[1,0]
	v_pk_add_f32 v[108:109], v[108:109], v[128:129] op_sel_hi:[1,0] neg_lo:[0,1] neg_hi:[0,1]
	v_pk_add_f32 v[110:111], v[110:111], v[128:129] op_sel_hi:[1,0] neg_lo:[0,1] neg_hi:[0,1]
	v_pk_add_f32 v[104:105], v[104:105], v[128:129] op_sel_hi:[1,0] neg_lo:[0,1] neg_hi:[0,1]
	v_pk_add_f32 v[106:107], v[106:107], v[128:129] op_sel_hi:[1,0] neg_lo:[0,1] neg_hi:[0,1]
	v_pk_add_f32 v[100:101], v[100:101], v[128:129] op_sel_hi:[1,0] neg_lo:[0,1] neg_hi:[0,1]
	v_pk_add_f32 v[102:103], v[102:103], v[128:129] op_sel_hi:[1,0] neg_lo:[0,1] neg_hi:[0,1]
	v_pk_add_f32 v[96:97], v[96:97], v[128:129] op_sel_hi:[1,0] neg_lo:[0,1] neg_hi:[0,1]
	v_pk_add_f32 v[98:99], v[98:99], v[128:129] op_sel_hi:[1,0] neg_lo:[0,1] neg_hi:[0,1]
; #define MFMA16(a, b, c) __builtin_amdgcn_mfma_f32_16x16x32_bf16((a), (b), (c), 0, 0, 0)
; static __device__ __forceinline__ void attn_item(const Params& p, int head, int j, char* smraw) {
;     ...
;     bf16x8 pf[2][2];
; #pragma unroll
;     for (int qt = 0; qt < 2; ++qt) {
;       float ps = 0.f;
; #pragma unroll
;       for (int kt = 0; kt < 4; ++kt)
; #pragma unroll
;         for (int r = 0; r < 4; ++r) {
;           const float pv = __builtin_amdgcn_exp2f(sacc[kt][qt][r]);
;           sacc[kt][qt][r] = pv; ps += pv;
;         }
;       lrun[qt] += ps;
; #pragma unroll
;       for (int k2 = 0; k2 < 2; ++k2) {
;         u32x4 pk = {cvtpk(sacc[2 * k2][qt][0], sacc[2 * k2][qt][1]), cvtpk(sacc[2 * k2][qt][2], sacc[2 * k2][qt][3]),
;                     cvtpk(sacc[2 * k2 + 1][qt][0], sacc[2 * k2 + 1][qt][1]), cvtpk(sacc[2 * k2 + 1][qt][2], sacc[2 * k2 + 1][qt][3])};
;         pf[qt][k2] = *(bf16x8*)&pk;
;       }
;     }
;     {
;       bf16x8 vf[2][4];
; #pragma unroll
;       for (int k2 = 0; k2 < 2; ++k2)
; #pragma unroll
;         for (int dt = 0; dt < 4; ++dt) vf[k2][dt] = *(const bf16x8*)(cV + (dt * 16 + l15) * 64 + (((k2 * 4 + quad) ^ (l15 & 7)) << 3));
;       __builtin_amdgcn_sched_barrier(0);
;       __builtin_amdgcn_s_setprio(1);
; #pragma unroll
;       for (int k2 = 0; k2 < 2; ++k2)
; #pragma unroll
;         for (int dt = 0; dt < 4; ++dt)
; #pragma unroll
;           for (int qt = 0; qt < 2; ++qt) oacc[dt][qt] = MFMA16(vf[k2][dt], pf[qt][k2], oacc[dt][qt]);
;       __builtin_amdgcn_s_setprio(0);
;       __builtin_amdgcn_sched_barrier(0);
;     }
;     ...
;     if (t + 2 < NT) ATT_STORE(rkA, rvA, 0);
.LBB0_384:
	v_exp_f32_e32 v163, v124
	v_exp_f32_e32 v159, v126
	v_exp_f32_e32 v151, v122
	v_exp_f32_e32 v162, v108
	v_exp_f32_e32 v160, v109
	v_exp_f32_e32 v158, v110
	v_exp_f32_e32 v156, v111
	v_exp_f32_e32 v154, v104
	v_exp_f32_e32 v152, v105
	v_exp_f32_e32 v150, v106
	v_exp_f32_e32 v148, v107
	v_exp_f32_e32 v146, v100
	v_exp_f32_e32 v126, v101
	v_exp_f32_e32 v124, v102
	v_exp_f32_e32 v122, v103
	ds_read_b128 v[100:103], v187 offset:40960
	ds_read_b128 v[104:107], v187 offset:43008
	ds_read_b128 v[108:111], v187 offset:45056
	ds_read_b128 v[192:195], v187 offset:47104
	ds_read_b128 v[196:199], v188 offset:40960
	ds_read_b128 v[200:203], v188 offset:43008
	ds_read_b128 v[204:207], v188 offset:45056
	ds_read_b128 v[208:211], v188 offset:47104
	v_exp_f32_e32 v161, v125
	v_exp_f32_e32 v157, v127
	v_exp_f32_e32 v155, v120
	v_exp_f32_e32 v153, v121
	v_exp_f32_e32 v149, v123
	v_exp_f32_e32 v147, v116
	v_exp_f32_e32 v127, v117
	v_exp_f32_e32 v125, v118
	v_exp_f32_e32 v123, v119
	v_exp_f32_e32 v121, v112
	v_exp_f32_e32 v119, v113
	v_exp_f32_e32 v117, v114
	v_exp_f32_e32 v113, v115
	v_exp_f32_e32 v120, v96
	v_exp_f32_e32 v118, v97
	v_exp_f32_e32 v116, v98
	v_exp_f32_e32 v112, v99
	v_cvt_pk_bf16_f32 v164, v163, v161
	v_cvt_pk_bf16_f32 v165, v159, v157
	v_cvt_pk_bf16_f32 v166, v155, v153
	v_cvt_pk_bf16_f32 v167, v151, v149
	v_cvt_pk_bf16_f32 v168, v147, v127
	v_cvt_pk_bf16_f32 v169, v125, v123
	v_cvt_pk_bf16_f32 v170, v121, v119
	v_cvt_pk_bf16_f32 v171, v117, v113
	v_cvt_pk_bf16_f32 v96, v162, v160
	v_cvt_pk_bf16_f32 v97, v158, v156
	v_cvt_pk_bf16_f32 v98, v154, v152
	v_cvt_pk_bf16_f32 v99, v150, v148
	v_cvt_pk_bf16_f32 v212, v146, v126
	v_cvt_pk_bf16_f32 v213, v124, v122
	v_cvt_pk_bf16_f32 v214, v120, v118
	v_cvt_pk_bf16_f32 v215, v116, v112
	s_setprio 1
	s_waitcnt lgkmcnt(7)
	v_mfma_f32_16x16x32_bf16 v[92:95], v[100:103], v[164:167], v[92:95]
	v_mfma_f32_16x16x32_bf16 v[88:91], v[100:103], v[96:99], v[88:91]
	v_add_f32_e32 v226, v160, v162
	v_add_f32_e32 v227, v161, v163
	s_waitcnt lgkmcnt(6)
	v_mfma_f32_16x16x32_bf16 v[84:87], v[104:107], v[164:167], v[84:87]
	v_add_f32_e32 v226, v158, v226
	v_add_f32_e32 v227, v159, v227
	v_mfma_f32_16x16x32_bf16 v[80:83], v[104:107], v[96:99], v[80:83]
	v_add_f32_e32 v226, v156, v226
	v_add_f32_e32 v227, v157, v227
	s_waitcnt lgkmcnt(5)
	v_mfma_f32_16x16x32_bf16 v[100:103], v[108:111], v[164:167], v[76:79]
	v_add_f32_e32 v226, v154, v226
	v_add_f32_e32 v227, v155, v227
	v_mfma_f32_16x16x32_bf16 v[104:107], v[108:111], v[96:99], v[72:75]
	v_add_f32_e32 v226, v152, v226
	v_add_f32_e32 v227, v153, v227
	s_waitcnt lgkmcnt(4)
	v_mfma_f32_16x16x32_bf16 v[108:111], v[192:195], v[164:167], v[68:71]
	v_add_f32_e32 v226, v150, v226
	v_add_f32_e32 v227, v151, v227
	v_mfma_f32_16x16x32_bf16 v[64:67], v[192:195], v[96:99], v[64:67]
	v_add_f32_e32 v226, v148, v226
	v_add_f32_e32 v227, v149, v227
	s_waitcnt lgkmcnt(3)
	v_mfma_f32_16x16x32_bf16 v[92:95], v[196:199], v[168:171], v[92:95]
	v_add_f32_e32 v226, v146, v226
	v_add_f32_e32 v227, v147, v227
	v_mfma_f32_16x16x32_bf16 v[76:79], v[196:199], v[212:215], v[88:91]
	v_add_f32_e32 v226, v126, v226
	v_add_f32_e32 v227, v127, v227
	s_waitcnt lgkmcnt(2)
	v_mfma_f32_16x16x32_bf16 v[88:91], v[200:203], v[168:171], v[84:87]
	v_add_f32_e32 v226, v124, v226
	v_add_f32_e32 v227, v125, v227
	v_mfma_f32_16x16x32_bf16 v[72:75], v[200:203], v[212:215], v[80:83]
	v_add_f32_e32 v226, v122, v226
	v_add_f32_e32 v227, v123, v227
	s_waitcnt lgkmcnt(1)
	v_mfma_f32_16x16x32_bf16 v[84:87], v[204:207], v[168:171], v[100:103]
	v_add_f32_e32 v226, v120, v226
	v_add_f32_e32 v227, v121, v227
	v_mfma_f32_16x16x32_bf16 v[68:71], v[204:207], v[212:215], v[104:107]
	v_add_f32_e32 v226, v118, v226
	v_add_f32_e32 v227, v119, v227
	s_waitcnt lgkmcnt(0)
	v_mfma_f32_16x16x32_bf16 v[80:83], v[208:211], v[168:171], v[108:111]
	v_add_f32_e32 v226, v116, v226
	v_add_f32_e32 v227, v117, v227
	v_mfma_f32_16x16x32_bf16 v[64:67], v[208:211], v[212:215], v[64:67]
	v_add_f32_e32 v226, v112, v226
	v_add_f32_e32 v227, v113, v227
	s_setprio 0
	v_pk_add_f32 v[144:145], v[144:145], v[226:227]
	s_andn2_b64 vcc, exec, s[50:51]
	s_cbranch_vccnz .LBB0_375
	ds_write_b128 v179, v[24:27]
	ds_write_b128 v180, v[28:31]
	ds_write_b128 v181, v[32:35]
	ds_write_b128 v182, v[36:39] offset:16384
	ds_write_b128 v183, v[40:43] offset:16384
	s_branch .LBB0_375

; __global__ void __launch_bounds__(256, 2) mega(Params p) {
;   __shared__ __attribute__((aligned(16))) char smem[73728];
	.amdhsa_kernel _Z4mega6Params
		.amdhsa_group_segment_fixed_size 73728
		.amdhsa_private_segment_fixed_size 0
		.amdhsa_kernarg_size 424
		.amdhsa_user_sgpr_count 2
		.amdhsa_user_sgpr_dispatch_ptr 0
		.amdhsa_user_sgpr_queue_ptr 0
		.amdhsa_user_sgpr_kernarg_segment_ptr 1
		.amdhsa_user_sgpr_dispatch_id 0
		.amdhsa_user_sgpr_kernarg_preload_length 0
		.amdhsa_user_sgpr_kernarg_preload_offset 0
		.amdhsa_user_sgpr_private_segment_size 0
		.amdhsa_uses_dynamic_stack 0
		.amdhsa_enable_private_segment 0
		.amdhsa_system_sgpr_workgroup_id_x 1
		.amdhsa_system_sgpr_workgroup_id_y 0
		.amdhsa_system_sgpr_workgroup_id_z 0
		.amdhsa_system_sgpr_workgroup_info 0
		.amdhsa_system_vgpr_workitem_id 2
		.amdhsa_next_free_vgpr 240
		.amdhsa_next_free_sgpr 100
		.amdhsa_accum_offset 240
		.amdhsa_reserve_vcc 1
		.amdhsa_float_round_mode_32 0
		.amdhsa_float_round_mode_16_64 0
		.amdhsa_float_denorm_mode_32 3
		.amdhsa_float_denorm_mode_16_64 3
		.amdhsa_dx10_clamp 1
		.amdhsa_ieee_mode 1
		.amdhsa_fp16_overflow 0
		.amdhsa_tg_split 0
		.amdhsa_exception_fp_ieee_invalid_op 0
		.amdhsa_exception_fp_denorm_src 0
		.amdhsa_exception_fp_ieee_div_zero 0
		.amdhsa_exception_fp_ieee_overflow 0
		.amdhsa_exception_fp_ieee_underflow 0
		.amdhsa_exception_fp_ieee_inexact 0
		.amdhsa_exception_int_div_zero 0
	.end_amdhsa_kernel

; __global__ void __launch_bounds__(256, 2) mega(Params p) {
;   __shared__ __attribute__((aligned(16))) char smem[73728];
amdhsa.kernels:
  - .agpr_count:     0
    .args:
      - .offset:         0
        .size:           168
        .value_kind:     by_value
      - .offset:         168
        .size:           4
        .value_kind:     hidden_block_count_x
      - .offset:         172
        .size:           4
        .value_kind:     hidden_block_count_y
      - .offset:         176
        .size:           4
        .value_kind:     hidden_block_count_z
      - .offset:         180
        .size:           2
        .value_kind:     hidden_group_size_x
      - .offset:         182
        .size:           2
        .value_kind:     hidden_group_size_y
      - .offset:         184
        .size:           2
        .value_kind:     hidden_group_size_z
      - .offset:         186
        .size:           2
        .value_kind:     hidden_remainder_x
      - .offset:         188
        .size:           2
        .value_kind:     hidden_remainder_y
      - .offset:         190
        .size:           2
        .value_kind:     hidden_remainder_z
      - .offset:         208
        .size:           8
        .value_kind:     hidden_global_offset_x
      - .offset:         216
        .size:           8
        .value_kind:     hidden_global_offset_y
      - .offset:         224
        .size:           8
        .value_kind:     hidden_global_offset_z
      - .offset:         232
        .size:           2
        .value_kind:     hidden_grid_dims
      - .offset:         256
        .size:           8
        .value_kind:     hidden_multigrid_sync_arg
    .group_segment_fixed_size: 73728
    .kernarg_segment_align: 8
    .kernarg_segment_size: 424
    .language:       OpenCL C
    .language_version:
      - 2
      - 0
    .max_flat_workgroup_size: 256
    .name:           _Z4mega6Params
    .private_segment_fixed_size: 0
    .sgpr_count:     106
    .sgpr_spill_count: 35
    .symbol:         _Z4mega6Params.kd
    .uniform_work_group_size: 1
    .uses_dynamic_stack: false
    .vgpr_count:     240
    .vgpr_spill_count: 0
    .wavefront_size: 64
